# v34 plus x to bf16 prologue loop unrolled to eight loads in flight
# baseline (speedup 1.0000x reference)
.Lx8_head:
	s_mul_i32 s100, s12, 7
	s_mov_b32 s101, 0x3fffff
	v_add_u32_e32 v38, s100, v0
	v_cmp_ge_i32_e32 vcc, s101, v38
	s_nop 1
	s_cmp_eq_u64 vcc, exec
	s_cbranch_scc0 .LBB0_469
	global_load_dwordx4 v[6:9], v[2:3], off
	v_lshl_add_u64 v[2:3], v[2:3], 0, s[6:7]
	global_load_dwordx4 v[10:13], v[2:3], off
	v_lshl_add_u64 v[2:3], v[2:3], 0, s[6:7]
	global_load_dwordx4 v[14:17], v[2:3], off
	v_lshl_add_u64 v[2:3], v[2:3], 0, s[6:7]
	global_load_dwordx4 v[18:21], v[2:3], off
	v_lshl_add_u64 v[2:3], v[2:3], 0, s[6:7]
	global_load_dwordx4 v[22:25], v[2:3], off
	v_lshl_add_u64 v[2:3], v[2:3], 0, s[6:7]
	global_load_dwordx4 v[26:29], v[2:3], off
	v_lshl_add_u64 v[2:3], v[2:3], 0, s[6:7]
	global_load_dwordx4 v[30:33], v[2:3], off
	v_lshl_add_u64 v[2:3], v[2:3], 0, s[6:7]
	global_load_dwordx4 v[34:37], v[2:3], off
	v_lshl_add_u64 v[2:3], v[2:3], 0, s[6:7]
	s_waitcnt vmcnt(7)
	v_cvt_pk_bf16_f32 v6, v6, v7
	v_cvt_pk_bf16_f32 v7, v8, v9
	global_store_dwordx2 v[4:5], v[6:7], off
	v_lshl_add_u64 v[4:5], v[4:5], 0, s[8:9]
	s_waitcnt vmcnt(7)
	v_cvt_pk_bf16_f32 v10, v10, v11
	v_cvt_pk_bf16_f32 v11, v12, v13
	global_store_dwordx2 v[4:5], v[10:11], off
	v_lshl_add_u64 v[4:5], v[4:5], 0, s[8:9]
	s_waitcnt vmcnt(7)
	v_cvt_pk_bf16_f32 v14, v14, v15
	v_cvt_pk_bf16_f32 v15, v16, v17
	global_store_dwordx2 v[4:5], v[14:15], off
	v_lshl_add_u64 v[4:5], v[4:5], 0, s[8:9]
	s_waitcnt vmcnt(7)
	v_cvt_pk_bf16_f32 v18, v18, v19
	v_cvt_pk_bf16_f32 v19, v20, v21
	global_store_dwordx2 v[4:5], v[18:19], off
	v_lshl_add_u64 v[4:5], v[4:5], 0, s[8:9]
	s_waitcnt vmcnt(7)
	v_cvt_pk_bf16_f32 v22, v22, v23
	v_cvt_pk_bf16_f32 v23, v24, v25
	global_store_dwordx2 v[4:5], v[22:23], off
	v_lshl_add_u64 v[4:5], v[4:5], 0, s[8:9]
	s_waitcnt vmcnt(7)
	v_cvt_pk_bf16_f32 v26, v26, v27
	v_cvt_pk_bf16_f32 v27, v28, v29
	global_store_dwordx2 v[4:5], v[26:27], off
	v_lshl_add_u64 v[4:5], v[4:5], 0, s[8:9]
	s_waitcnt vmcnt(7)
	v_cvt_pk_bf16_f32 v30, v30, v31
	v_cvt_pk_bf16_f32 v31, v32, v33
	global_store_dwordx2 v[4:5], v[30:31], off
	v_lshl_add_u64 v[4:5], v[4:5], 0, s[8:9]
	s_waitcnt vmcnt(7)
	v_cvt_pk_bf16_f32 v34, v34, v35
	v_cvt_pk_bf16_f32 v35, v36, v37
	global_store_dwordx2 v[4:5], v[34:35], off
	v_lshl_add_u64 v[4:5], v[4:5], 0, s[8:9]
	v_add_u32_e32 v0, s100, v0
	v_add_u32_e32 v0, s12, v0
	v_cmp_lt_i32_e32 vcc, s101, v0
	s_or_b64 s[30:31], vcc, s[30:31]
	s_andn2_b64 exec, exec, s[30:31]
	s_cbranch_execnz .Lx8_head
	s_branch .LBB0_7
